# LRU mt-loop body rewritten by hand: packed f32 math, d16_hi LDS loads/stores, folded constants (134 vs 205 instr per tile)
# speedup vs baseline: 1.1403x; 1.0093x over previous
.Lstg_nopf:
	v_mov_b32_e32 v240, 0xbfb8aa3b
	v_mov_b32_e32 v241, 0xbfb8aa3b
	v_mul_f32_e32 v242, 0xbfb8aa3b, v45
	v_mul_f32_e32 v243, 0xbfb8aa3b, v45
	v_mul_f32_e32 v244, 0xbfb8aa3b, v46
	v_mul_f32_e32 v245, 0xbfb8aa3b, v46
	v_mul_f32_e32 v246, 0x3fb8aa3b, v48
	v_mul_f32_e32 v247, 0x3fb8aa3b, v48
	v_mov_b32_e32 v232, 0
	v_mov_b32_e32 v233, 0
	v_mov_b32_e32 v234, 0
	v_mov_b32_e32 v235, 0
	v_mov_b32_e32 v236, 0
	v_mov_b32_e32 v237, 0
	v_mov_b32_e32 v238, 0
	v_mov_b32_e32 v239, 0
	v_add_u32_e32 v157, 0x12100, v53
.LBB0_409:
	ds_read_b128 v[60:63], v51
	ds_read_b128 v[64:67], v51 offset:64
	ds_read_u16_d16_hi v232, v52
	ds_read_u16_d16_hi v233, v52 offset:272
	ds_read_u16_d16_hi v234, v52 offset:544
	ds_read_u16_d16_hi v235, v52 offset:816
	ds_read_u16_d16_hi v236, v157
	ds_read_u16_d16_hi v237, v157 offset:256
	ds_read_u16_d16_hi v238, v157 offset:512
	ds_read_u16_d16_hi v239, v157 offset:768
	s_waitcnt lgkmcnt(9)
	v_mfma_f32_16x16x32_bf16 v[36:39], v[60:63], v[0:3], 0
	v_mfma_f32_16x16x32_bf16 v[56:59], v[60:63], v[8:11], 0
	ds_read_b128 v[60:63], v51 offset:128
	s_waitcnt lgkmcnt(9)
	v_mfma_f32_16x16x32_bf16 v[36:39], v[64:67], v[4:7], v[36:39]
	v_mfma_f32_16x16x32_bf16 v[56:59], v[64:67], v[12:15], v[56:59]
	ds_read_b128 v[64:67], v51 offset:192
	s_waitcnt lgkmcnt(1)
	v_mfma_f32_16x16x32_bf16 v[36:39], v[60:63], v[16:19], v[36:39]
	v_mfma_f32_16x16x32_bf16 v[56:59], v[60:63], v[24:27], v[56:59]
	s_waitcnt lgkmcnt(0)
	v_mfma_f32_16x16x32_bf16 v[36:39], v[64:67], v[20:23], v[36:39]
	v_mfma_f32_16x16x32_bf16 v[56:59], v[64:67], v[28:31], v[56:59]
	v_add_u32_e32 v51, 0x1100, v51
	v_add_u32_e32 v52, 0x1100, v52
	v_add_u32_e32 v157, 0x1000, v157
	v_pk_mul_f32 v[230:231], v[236:237], v[240:241]
	v_pk_mul_f32 v[216:217], v[238:239], v[240:241]
	v_exp_f32_e32 v230, v230
	v_exp_f32_e32 v231, v231
	v_exp_f32_e32 v216, v216
	v_exp_f32_e32 v217, v217
	v_pk_add_f32 v[230:231], v[230:231], 1.0 op_sel_hi:[1,0]
	v_pk_add_f32 v[216:217], v[216:217], 1.0 op_sel_hi:[1,0]
	v_rcp_f32_e32 v230, v230
	v_rcp_f32_e32 v231, v231
	v_rcp_f32_e32 v216, v216
	v_rcp_f32_e32 v217, v217
	v_pk_fma_f32 v[212:213], v[36:37], v[240:241], v[242:243]
	v_pk_fma_f32 v[214:215], v[38:39], v[240:241], v[242:243]
	v_pk_fma_f32 v[220:221], v[56:57], v[240:241], v[244:245]
	v_pk_fma_f32 v[222:223], v[58:59], v[240:241], v[244:245]
	v_exp_f32_e32 v212, v212
	v_exp_f32_e32 v213, v213
	v_exp_f32_e32 v214, v214
	v_exp_f32_e32 v215, v215
	v_exp_f32_e32 v220, v220
	v_exp_f32_e32 v221, v221
	v_exp_f32_e32 v222, v222
	v_exp_f32_e32 v223, v223
	v_pk_add_f32 v[212:213], v[212:213], 1.0 op_sel_hi:[1,0]
	v_pk_add_f32 v[214:215], v[214:215], 1.0 op_sel_hi:[1,0]
	v_pk_add_f32 v[220:221], v[220:221], 1.0 op_sel_hi:[1,0]
	v_pk_add_f32 v[222:223], v[222:223], 1.0 op_sel_hi:[1,0]
	v_rcp_f32_e32 v212, v212
	v_rcp_f32_e32 v213, v213
	v_rcp_f32_e32 v214, v214
	v_rcp_f32_e32 v215, v215
	v_rcp_f32_e32 v220, v220
	v_rcp_f32_e32 v221, v221
	v_rcp_f32_e32 v222, v222
	v_rcp_f32_e32 v223, v223
	v_pk_mul_f32 v[226:227], v[212:213], v[246:247]
	v_pk_mul_f32 v[228:229], v[214:215], v[246:247]
	v_pk_mul_f32 v[220:221], v[220:221], v[232:233]
	v_pk_mul_f32 v[222:223], v[222:223], v[234:235]
	v_exp_f32_e32 v226, v226
	v_exp_f32_e32 v227, v227
	v_exp_f32_e32 v228, v228
	v_exp_f32_e32 v229, v229
	v_pk_fma_f32 v[166:167], v[226:227], v[226:227], 1.0 op_sel_hi:[1,1,0] neg_lo:[1,0,0] neg_hi:[1,0,0]
	v_pk_fma_f32 v[168:169], v[228:229], v[228:229], 1.0 op_sel_hi:[1,1,0] neg_lo:[1,0,0] neg_hi:[1,0,0]
	v_sqrt_f32_e32 v166, v166
	v_sqrt_f32_e32 v167, v167
	v_sqrt_f32_e32 v168, v168
	v_sqrt_f32_e32 v169, v169
	v_pk_mul_f32 v[166:167], v[166:167], v[220:221]
	v_pk_mul_f32 v[168:169], v[168:169], v[222:223]
	v_fmac_f32_e32 v167, v227, v166
	v_mul_f32_e32 v227, v227, v226
	v_fmac_f32_e32 v168, v228, v167
	v_mul_f32_e32 v228, v228, v227
	v_fmac_f32_e32 v169, v229, v168
	v_mul_f32_e32 v229, v229, v228
	ds_bpermute_b32 v40, v47, v229
	ds_bpermute_b32 v41, v47, v169
	s_waitcnt lgkmcnt(0)
	v_mul_f32_e32 v40, v229, v40
	v_fma_f32 v41, v229, v41, v169
	v_cndmask_b32_e32 v225, v40, v229, vcc
	v_cndmask_b32_e32 v126, v41, v169, vcc
	ds_bpermute_b32 v40, v49, v225
	ds_bpermute_b32 v41, v49, v126
	s_waitcnt lgkmcnt(0)
	v_mul_f32_e32 v40, v225, v40
	v_fma_f32 v41, v225, v41, v126
	v_cndmask_b32_e64 v185, v225, v40, s[38:39]
	v_cndmask_b32_e64 v186, v126, v41, s[38:39]
	v_fmac_f32_e32 v186, v44, v185
	ds_bpermute_b32 v34, v47, v186
	ds_bpermute_b32 v35, v47, v185
	ds_bpermute_b32 v187, v50, v186
	ds_bpermute_b32 v156, v50, v185
	s_waitcnt lgkmcnt(0)
	v_cndmask_b32_e32 v34, v34, v44, vcc
	v_cndmask_b32_e64 v35, v35, 1.0, vcc
	v_mul_f32_e32 v35, v43, v35
	v_mov_b32_e32 v44, v187
	v_mul_f32_e32 v43, v43, v156
	v_pk_fma_f32 v[166:167], v[226:227], v[34:35], v[166:167] op_sel_hi:[1,0,1]
	v_pk_fma_f32 v[168:169], v[228:229], v[34:35], v[168:169] op_sel_hi:[1,0,1]
	v_pk_mul_f32 v[226:227], v[226:227], v[34:35] op_sel:[0,1] op_sel_hi:[1,1]
	v_pk_mul_f32 v[228:229], v[228:229], v[34:35] op_sel:[0,1] op_sel_hi:[1,1]
	v_pk_mul_f32 v[166:167], v[166:167], v[230:231]
	v_pk_mul_f32 v[168:169], v[168:169], v[216:217]
	v_pk_mul_f32 v[226:227], v[226:227], v[230:231]
	v_pk_mul_f32 v[228:229], v[228:229], v[216:217]
	v_cvt_pk_bf16_f32 v54, v166, v167
	v_cvt_pk_bf16_f32 v55, v168, v169
	v_cvt_pk_bf16_f32 v222, v226, v227
	v_cvt_pk_bf16_f32 v223, v228, v229
	global_store_short v170, v54, s[62:63]
	global_store_short_d16_hi v170, v54, s[62:63] offset:2048
	global_store_short v171, v55, s[62:63]
	global_store_short_d16_hi v171, v55, s[62:63] offset:2048
	global_store_short v170, v222, s[90:91]
	global_store_short_d16_hi v170, v222, s[90:91] offset:2048
	global_store_short v171, v223, s[90:91]
	global_store_short_d16_hi v171, v223, s[90:91] offset:2048
	v_add_u32_e32 v170, 0x8000, v170
	v_add_u32_e32 v171, 0x8000, v171
	s_add_i32 s5, s5, 1
	s_cmp_lt_i32 s5, s68
	s_cbranch_scc1 .LBB0_409
	v_cmp_eq_u32_e32 vcc, 0, v42
	s_and_saveexec_b64 s[0:1], vcc
	s_cbranch_execz .LBB0_346
	s_branch .LBB0_412
